# baseline (speedup 1.0000x reference)
.LBB0_312:
	s_mul_i32 s78, s98, 0x4800
	v_or_b32_e32 v0, s78, v205
	v_add_u32_e32 v2, v0, v207
	ds_read_b128 v[60:63], v2
	ds_read_b128 v[64:67], v2 offset:64
	v_add_u32_e32 v0, v0, v222
	ds_read_b128 v[72:75], v0
	ds_read_b128 v[92:95], v0 offset:64
	ds_read_b128 v[100:103], v2 offset:4608
	ds_read_b128 v[104:107], v2 offset:4672
	ds_read_b128 v[112:115], v2 offset:6912
	ds_read_b128 v[156:159], v2 offset:6976
	s_waitcnt vmcnt(3) lgkmcnt(5)
	s_setprio 3
	v_mfma_f32_16x16x32_bf16 v[96:99], v[72:75], v[20:23], 0
	s_cmp_eq_u32 s74, s85
	s_cselect_b64 s[6:7], -1, 0
	s_or_b64 s[6:7], s[18:19], s[6:7]
	v_mfma_f32_16x16x32_bf16 v[68:71], v[60:63], v[20:23], 0
	s_lshl_b32 s0, s74, 6
	s_cmp_lt_i32 s0, s94
	s_cselect_b64 s[8:9], -1, 0
	s_waitcnt lgkmcnt(3)
	v_mfma_f32_16x16x32_bf16 v[108:111], v[100:103], v[20:23], 0
	s_and_b64 s[8:9], s[68:69], s[8:9]
	s_or_b64 s[64:65], s[6:7], s[8:9]
	v_or_b32_e32 v245, s0, v206
	s_waitcnt lgkmcnt(1)
	v_mfma_f32_16x16x32_bf16 v[160:163], v[112:115], v[20:23], 0
	s_and_b64 vcc, exec, s[64:65]
	s_waitcnt vmcnt(1)
	v_mfma_f32_16x16x32_bf16 v[60:63], v[60:63], v[28:31], 0
	v_mfma_f32_16x16x32_bf16 v[164:167], v[72:75], v[28:31], 0
	v_mfma_f32_16x16x32_bf16 v[100:103], v[100:103], v[28:31], 0
	v_mfma_f32_16x16x32_bf16 v[196:199], v[112:115], v[28:31], 0
	v_mfma_f32_16x16x32_bf16 v[120:123], v[64:67], v[24:27], v[68:71]
	v_mfma_f32_16x16x32_bf16 v[116:119], v[92:95], v[24:27], v[96:99]
	v_mfma_f32_16x16x32_bf16 v[112:115], v[104:107], v[24:27], v[108:111]
	s_waitcnt lgkmcnt(0)
	v_mfma_f32_16x16x32_bf16 v[108:111], v[156:159], v[24:27], v[160:163]
	s_waitcnt vmcnt(0)
	v_mfma_f32_16x16x32_bf16 v[72:75], v[64:67], v[32:35], v[60:63]
	v_mfma_f32_16x16x32_bf16 v[68:71], v[92:95], v[32:35], v[164:167]
	v_mfma_f32_16x16x32_bf16 v[64:67], v[104:107], v[32:35], v[100:103]
	v_mfma_f32_16x16x32_bf16 v[60:63], v[156:159], v[32:35], v[196:199]
	s_setprio 0
	s_cbranch_vccz .LBB0_474
	v_add_u32_e32 v92, -1, v237
	s_orn2_b64 s[6:7], s[14:15], s[12:13]
	v_add_u32_e32 v93, 1, v239
	v_mov_b32_e32 v94, 0x80000001
	v_cndmask_b32_e64 v92, v92, v236, s[12:13]
	v_cndmask_b32_e64 v93, v93, v94, s[6:7]
	v_sub_u32_e32 v92, v92, v93
	v_sub_u32_e32 v93, v245, v93
	v_add_u32_e32 v94, 0, v93
	v_cmp_gt_u32_e32 vcc, v94, v92
	v_add_u32_e32 v95, 1, v93
	v_cmp_gt_u32_e64 s[8:9], v95, v92
	v_add_u32_e32 v0, 2, v93
	v_cmp_gt_u32_e64 s[10:11], v0, v92
	v_cndmask_b32_e32 v120, v120, v193, vcc
	v_add_u32_e32 v94, 3, v93
	v_cmp_gt_u32_e32 vcc, v94, v92
	v_cndmask_b32_e64 v121, v121, v193, s[8:9]
	v_add_u32_e32 v95, 16, v93
	v_cmp_gt_u32_e64 s[8:9], v95, v92
	v_cndmask_b32_e64 v122, v122, v193, s[10:11]
	v_add_u32_e32 v0, 17, v93
	v_cmp_gt_u32_e64 s[10:11], v0, v92
	v_cndmask_b32_e32 v123, v123, v193, vcc
	v_add_u32_e32 v94, 18, v93
	v_cmp_gt_u32_e32 vcc, v94, v92
	v_cndmask_b32_e64 v116, v116, v193, s[8:9]
	v_add_u32_e32 v95, 19, v93
	v_cmp_gt_u32_e64 s[8:9], v95, v92
	v_cndmask_b32_e64 v117, v117, v193, s[10:11]
	v_add_u32_e32 v0, 32, v93
	v_cmp_gt_u32_e64 s[10:11], v0, v92
	v_cndmask_b32_e32 v118, v118, v193, vcc
	v_add_u32_e32 v94, 33, v93
	v_cmp_gt_u32_e32 vcc, v94, v92
	v_cndmask_b32_e64 v119, v119, v193, s[8:9]
	v_add_u32_e32 v95, 34, v93
	v_cmp_gt_u32_e64 s[8:9], v95, v92
	v_cndmask_b32_e64 v112, v112, v193, s[10:11]
	v_add_u32_e32 v0, 35, v93
	v_cmp_gt_u32_e64 s[10:11], v0, v92
	v_cndmask_b32_e32 v113, v113, v193, vcc
	v_add_u32_e32 v94, 48, v93
	v_cmp_gt_u32_e32 vcc, v94, v92
	v_cndmask_b32_e64 v114, v114, v193, s[8:9]
	v_add_u32_e32 v95, 49, v93
	v_cmp_gt_u32_e64 s[8:9], v95, v92
	v_cndmask_b32_e64 v115, v115, v193, s[10:11]
	v_add_u32_e32 v0, 50, v93
	v_cmp_gt_u32_e64 s[10:11], v0, v92
	v_cndmask_b32_e32 v108, v108, v193, vcc
	v_add_u32_e32 v94, 51, v93
	v_cmp_gt_u32_e32 vcc, v94, v92
	v_cndmask_b32_e64 v109, v109, v193, s[8:9]
	v_cndmask_b32_e64 v110, v110, v193, s[10:11]
	v_cndmask_b32_e32 v111, v111, v193, vcc

.LBB0_748:
	s_lshr_b32 s13, s6, 2
	s_and_b32 s12, s6, 3
	s_cmp_eq_u32 s13, s38
	s_cselect_b64 s[10:11], -1, 0
	s_cmp_lg_u32 s13, s38
	s_cselect_b64 s[6:7], -1, 0
	v_cmp_le_i32_e32 vcc, s12, v117
	s_or_b64 s[14:15], s[6:7], vcc
	v_mov_b32_e32 v66, v126
	v_mov_b32_e32 v67, v127
	s_and_saveexec_b64 s[6:7], s[14:15]
	s_cbranch_execz .LBB0_761
	s_lshl_b32 s13, 1, s13
	v_and_b32_e32 v66, s13, v120
	v_cmp_ne_u32_e32 vcc, 0, v66
	v_and_b32_e32 v66, s13, v121
	s_or_b64 s[96:97], s[10:11], vcc
	v_cmp_ne_u32_e64 s[98:99], 0, v66
	s_or_b64 s[14:15], s[96:97], s[98:99]
	v_cndmask_b32_e64 v66, 0, 1, s[14:15]
	v_cmp_ne_u32_e32 vcc, 0, v66
	s_cbranch_vccz .LBB0_759
	s_mulk_i32 s9, 0x4800
	v_or_b32_e32 v66, s9, v132
	v_add_u32_e32 v147, v66, v133
	ds_read_b128 v[66:69], v147
	ds_read_b128 v[82:85], v147 offset:64
	ds_read_b128 v[74:77], v147 offset:2304
	ds_read_b128 v[86:89], v147 offset:2368
	ds_read_b128 v[90:93], v147 offset:4608
	ds_read_b128 v[148:151], v147 offset:4672
	ds_read_b128 v[152:155], v147 offset:6912
	ds_read_b128 v[156:159], v147 offset:6976
	s_waitcnt vmcnt(3) lgkmcnt(7)
	s_setprio 3
	v_mfma_f32_16x16x32_bf16 v[70:73], v[66:69], v[2:5], 0
	v_cmp_eq_u32_e32 vcc, s12, v117
	s_and_b64 s[12:13], s[10:11], vcc
	s_waitcnt lgkmcnt(5)
	v_mfma_f32_16x16x32_bf16 v[78:81], v[74:77], v[2:5], 0
	s_waitcnt lgkmcnt(3)
	v_mfma_f32_16x16x32_bf16 v[94:97], v[90:93], v[2:5], 0
	s_waitcnt lgkmcnt(1)
	v_mfma_f32_16x16x32_bf16 v[160:163], v[152:155], v[2:5], 0
	s_waitcnt vmcnt(1)
	v_mfma_f32_16x16x32_bf16 v[164:167], v[66:69], v[14:17], 0
	v_mfma_f32_16x16x32_bf16 v[204:207], v[74:77], v[14:17], 0
	v_mfma_f32_16x16x32_bf16 v[208:211], v[90:93], v[14:17], 0
	v_mfma_f32_16x16x32_bf16 v[152:155], v[152:155], v[14:17], 0
	v_mfma_f32_16x16x32_bf16 v[74:77], v[82:85], v[6:9], v[70:73]
	v_mfma_f32_16x16x32_bf16 v[70:73], v[86:89], v[6:9], v[78:81]
	v_mfma_f32_16x16x32_bf16 v[66:69], v[148:151], v[6:9], v[94:97]
	s_waitcnt lgkmcnt(0)
	v_mfma_f32_16x16x32_bf16 v[78:81], v[156:159], v[6:9], v[160:163]
	s_waitcnt vmcnt(0)
	v_mfma_f32_16x16x32_bf16 v[94:97], v[82:85], v[18:21], v[164:167]
	v_mfma_f32_16x16x32_bf16 v[90:93], v[86:89], v[18:21], v[204:207]
	v_mfma_f32_16x16x32_bf16 v[86:89], v[148:151], v[18:21], v[208:211]
	v_mfma_f32_16x16x32_bf16 v[82:85], v[156:159], v[18:21], v[152:155]
	s_setprio 0
	s_and_saveexec_b64 s[14:15], s[12:13]
	s_cbranch_execz .LBB0_752
	s_nop 0
	v_mov_b32_e32 v78, s43
	v_cndmask_b32_e64 v78, v74, v78, s[50:51]
	v_cndmask_b32_e64 v74, v78, v74, s[52:53]
	v_mov_b32_e32 v78, s43
	v_cndmask_b32_e64 v70, v70, v78, s[58:59]
	v_cndmask_b32_e64 v66, v66, v78, s[66:67]
	v_mov_b32_e32 v78, 0xf149f2ca
	v_cndmask_b32_e64 v75, v193, v75, s[52:53]
	v_cndmask_b32_e64 v76, v76, v193, s[54:55]
	v_cndmask_b32_e64 v77, v77, v193, s[56:57]
	v_cndmask_b32_e64 v71, v71, v193, s[60:61]
	v_cndmask_b32_e64 v72, v72, v193, s[62:63]
	v_cndmask_b32_e64 v73, v73, v193, s[64:65]
	v_cndmask_b32_e64 v67, v67, v193, s[68:69]
	v_cndmask_b32_e64 v68, v68, v193, s[70:71]
	v_cndmask_b32_e64 v69, v69, v193, s[72:73]
	v_mov_b32_e32 v79, v78
	v_mov_b32_e32 v80, v78
	v_mov_b32_e32 v81, v78

.LBB0_776:
	v_cmp_le_i32_e32 vcc, s35, v101
	s_xor_b64 s[6:7], s[38:39], -1
	s_and_b64 s[10:11], vcc, s[6:7]
	s_and_saveexec_b64 s[6:7], s[10:11]
	s_cbranch_execz .LBB0_778
	s_mul_i32 s10, s26, 0x4800
	v_add_u32_e32 v169, s10, v154
	v_add_u32_e32 v0, v169, v153
	ds_read_b128 v[66:69], v0
	ds_read_b128 v[74:77], v0 offset:64
	ds_read_b128 v[78:81], v0 offset:2304
	ds_read_b128 v[82:85], v0 offset:2368
	ds_read_b128 v[90:93], v0 offset:4608
	ds_read_b128 v[108:111], v0 offset:4672
	ds_read_b128 v[116:119], v0 offset:6912
	ds_read_b128 v[120:123], v0 offset:6976
	s_waitcnt vmcnt(3) lgkmcnt(7)
	s_setprio 3
	v_mfma_f32_16x16x32_bf16 v[70:73], v[66:69], v[2:5], 0
	v_cmp_lt_i32_e32 vcc, v184, v182
	s_mov_b32 s30, 0x3f317218
	v_mov_b32_e32 v214, v1
	s_waitcnt vmcnt(2) lgkmcnt(6)
	v_mfma_f32_16x16x32_bf16 v[130:133], v[74:77], v[6:9], v[70:73]
	v_cndmask_b32_e32 v0, v180, v184, vcc
	v_lshlrev_b32_e32 v204, 2, v0
	v_cmp_lt_i32_e32 vcc, v183, v182
	s_waitcnt lgkmcnt(1)
	v_mfma_f32_16x16x32_bf16 v[126:129], v[116:119], v[2:5], 0
	v_mov_b32_e32 v216, v1
	s_nop 1
	v_mul_f32_e32 v70, 0x3e000000, v130
	v_mul_f32_e64 v71, |v70|, s41
	v_exp_f32_e32 v71, v71
	v_max_f32_e32 v70, 0, v70
	v_cndmask_b32_e32 v72, v180, v183, vcc
	v_mfma_f32_16x16x32_bf16 v[112:115], v[90:93], v[2:5], 0
	v_add_f32_e32 v0, 1.0, v71
	v_log_f32_e32 v0, v0
	v_lshlrev_b32_e32 v203, 2, v72
	s_waitcnt vmcnt(1)
	v_mfma_f32_16x16x32_bf16 v[134:137], v[90:93], v[14:17], 0
	v_cmp_ne_u32_e32 vcc, 0, v168
	v_fmac_f32_e32 v70, 0x3f317218, v0
	v_mul_f32_e32 v0, 0x3e000000, v131
	v_fma_f32 v145, v130, s4, -v70
	v_add_f32_e32 v212, 0, v70
	v_mul_f32_e64 v90, |v0|, s41
	s_waitcnt lgkmcnt(0)
	v_mfma_f32_16x16x32_bf16 v[70:73], v[120:123], v[6:9], v[126:129]
	v_max_f32_e32 v0, 0, v0
	s_or_b64 s[10:11], s[48:49], vcc
	s_or_b64 s[94:95], s[56:57], vcc
	v_mfma_f32_16x16x32_bf16 v[86:89], v[78:81], v[2:5], 0
	v_exp_f32_e32 v126, v90
	s_nop 2
	v_mul_f32_e32 v127, 0x3e000000, v70
	s_or_b64 s[16:17], s[64:65], vcc
	v_mfma_f32_16x16x32_bf16 v[78:81], v[78:81], v[14:17], 0
	v_add_f32_e32 v126, 1.0, v126
	s_or_b64 s[14:15], s[54:55], vcc
	s_or_b64 s[18:19], s[68:69], vcc
	v_mfma_f32_16x16x32_bf16 v[90:93], v[82:85], v[6:9], v[86:89]
	s_or_b64 s[96:97], s[58:59], vcc
	v_cndmask_b32_e64 v226, v193, v145, s[94:95]
	s_or_b64 s[98:99], s[62:63], vcc
	v_mul_f32_e64 v86, |v127|, s41
	v_exp_f32_e32 v128, v86
	v_mfma_f32_16x16x32_bf16 v[86:89], v[108:111], v[6:9], v[112:115]
	v_mov_b32_e32 v145, v1
	s_or_b64 s[20:21], s[80:81], vcc
	s_or_b64 s[22:23], s[84:85], vcc
	v_log_f32_e32 v112, v126
	s_waitcnt vmcnt(0)
	v_mfma_f32_16x16x32_bf16 v[82:85], v[82:85], v[18:21], v[78:81]
	v_add_f32_e32 v113, 1.0, v128
	v_log_f32_e32 v113, v113
	v_fmac_f32_e32 v0, 0x3f317218, v112
	v_mfma_f32_16x16x32_bf16 v[78:81], v[108:111], v[18:21], v[134:137]
	v_mul_f32_e32 v109, 0x3e000000, v132
	v_mul_f32_e64 v110, |v109|, s41
	v_exp_f32_e32 v110, v110
	v_cndmask_b32_e64 v108, 0, v0, s[10:11]
	v_fma_f32 v0, v131, s4, -v0
	v_mul_f32_e32 v111, 0x3e000000, v133
	v_cndmask_b32_e64 v205, v193, v0, s[10:11]
	v_max_f32_e32 v0, 0, v109
	v_add_f32_e32 v109, 1.0, v110
	v_mul_f32_e64 v110, |v111|, s41
	v_log_f32_e32 v109, v109
	v_exp_f32_e32 v112, v110
	s_or_b64 s[10:11], s[50:51], vcc
	v_max_f32_e32 v114, 0, v127
	v_fmac_f32_e32 v0, 0x3f317218, v109
	v_add_f32_e32 v109, 1.0, v112
	v_log_f32_e32 v109, v109
	v_cndmask_b32_e64 v110, 0, v0, s[10:11]
	v_fma_f32 v0, v132, s4, -v0
	v_cndmask_b32_e64 v206, v193, v0, s[10:11]
	v_max_f32_e32 v0, 0, v111
	v_fmac_f32_e32 v0, 0x3f317218, v109
	v_mul_f32_e32 v109, 0x3e000000, v90
	v_mul_f32_e64 v111, |v109|, s41
	v_exp_f32_e32 v111, v111
	s_or_b64 s[10:11], s[52:53], vcc
	v_cndmask_b32_e64 v112, 0, v0, s[10:11]
	v_fma_f32 v0, v133, s4, -v0
	v_cndmask_b32_e64 v207, v193, v0, s[10:11]
	v_add_f32_e32 v0, 1.0, v111
	v_mul_f32_e32 v111, 0x3e000000, v91
	v_mfma_f32_16x16x32_bf16 v[66:69], v[66:69], v[14:17], 0
	v_fmac_f32_e32 v114, 0x3f317218, v113
	v_mul_f32_e64 v113, |v111|, s41
	v_log_f32_e32 v0, v0
	v_mfma_f32_16x16x32_bf16 v[116:119], v[116:119], v[14:17], 0
	v_exp_f32_e32 v113, v113
	s_or_b64 s[10:11], s[60:61], vcc
	v_cndmask_b32_e64 v132, 0, v212, s[94:95]
	v_mfma_f32_16x16x32_bf16 v[66:69], v[74:77], v[18:21], v[66:69]
	v_mov_b32_e32 v212, v1
	s_or_b64 s[12:13], s[86:87], vcc
	s_or_b64 s[24:25], s[88:89], vcc
	v_mfma_f32_16x16x32_bf16 v[74:77], v[120:123], v[18:21], v[116:119]
	s_setprio 0
	v_fma_f32 v70, v70, s4, -v114
	v_cndmask_b32_e32 v70, v193, v70, vcc
	s_nop 0
	v_max_f32_e32 v118, 0, v109
	v_fmac_f32_e32 v118, 0x3f317218, v0
	v_add_f32_e32 v0, 1.0, v113
	v_mul_f32_e32 v113, 0x3e000000, v92
	v_log_f32_e32 v109, v0
	v_mul_f32_e64 v0, |v113|, s41
	v_exp_f32_e32 v115, v0
	v_max_f32_e32 v0, 0, v111
	v_mul_f32_e32 v148, 0x3f317218, v109
	v_max_f32_e32 v150, 0, v113
	v_add_f32_e32 v109, 1.0, v115
	v_log_f32_e32 v196, v109
	v_mul_f32_e32 v109, 0x3e000000, v93
	v_mul_f32_e64 v111, |v109|, s41
	v_mul_f32_e32 v113, 0x3e000000, v86
	v_exp_f32_e32 v111, v111
	v_mul_f32_e64 v115, |v113|, s41
	v_exp_f32_e32 v115, v115
	v_max_f32_e32 v198, 0, v109
	v_add_f32_e32 v109, 1.0, v111
	v_log_f32_e32 v210, v109
	v_add_f32_e32 v109, 1.0, v115
	v_mul_f32_e32 v111, 0x3e000000, v87
	v_log_f32_e32 v109, v109
	v_mul_f32_e64 v115, |v111|, s41
	v_exp_f32_e32 v115, v115
	v_max_f32_e32 v134, 0, v113
	v_fmac_f32_e32 v134, 0x3f317218, v109
	v_mul_f32_e32 v109, 0x3e000000, v88
	v_fma_f32 v113, v86, s4, -v134
	v_add_f32_e32 v86, 1.0, v115
	v_mul_f32_e64 v115, |v109|, s41
	v_log_f32_e32 v86, v86
	v_exp_f32_e32 v115, v115
	v_max_f32_e32 v144, 0, v111
	v_max_f32_e32 v138, 0, v109
	v_mul_f32_e32 v146, 0x3f317218, v86
	v_add_f32_e32 v86, 1.0, v115
	v_log_f32_e32 v142, v86
	v_mul_f32_e32 v86, 0x3e000000, v89
	v_mul_f32_e64 v109, |v86|, s41
	v_mul_f32_e32 v111, 0x3e000000, v71
	v_exp_f32_e32 v109, v109
	v_mul_f32_e64 v115, |v111|, s41
	v_exp_f32_e32 v115, v115
	v_max_f32_e32 v136, 0, v86
	v_add_f32_e32 v86, 1.0, v109
	v_log_f32_e32 v140, v86
	v_add_f32_e32 v86, 1.0, v115
	v_mul_f32_e32 v115, 0x3e000000, v72
	v_log_f32_e32 v109, v86
	v_mul_f32_e64 v86, |v115|, s41
	v_exp_f32_e32 v116, v86
	v_max_f32_e32 v86, 0, v111
	v_mul_f32_e32 v111, 0x3e000000, v66
	v_max_f32_e32 v120, 0, v115
	v_mul_f32_e64 v115, |v111|, s41
	v_exp_f32_e32 v115, v115
	v_mul_f32_e32 v126, 0x3f317218, v109
	v_add_f32_e32 v109, 1.0, v116
	v_log_f32_e32 v122, v109
	v_mul_f32_e32 v109, 0x3e000000, v73
	v_mul_f32_e64 v116, |v109|, s41
	v_max_f32_e32 v128, 0, v109
	v_add_f32_e32 v109, 1.0, v115
	v_exp_f32_e32 v116, v116
	v_log_f32_e32 v109, v109
	v_max_f32_e32 v111, 0, v111
	v_fma_f32 v90, v90, s4, -v118
	v_add_f32_e32 v115, 1.0, v116
	v_fmac_f32_e32 v111, 0x3f317218, v109
	v_mul_f32_e32 v109, 0x3e000000, v67
	v_log_f32_e32 v130, v115
	v_mul_f32_e64 v115, |v109|, s41
	v_exp_f32_e32 v115, v115
	v_fma_f32 v208, v66, s4, -v111
	v_add_f32_e32 v133, 0, v111
	v_mul_f32_e32 v111, 0x3e000000, v68
	v_add_f32_e32 v66, 1.0, v115
	v_log_f32_e32 v66, v66
	v_mul_f32_e64 v115, |v111|, s41
	v_exp_f32_e32 v115, v115
	v_max_f32_e32 v109, 0, v109
	v_fmac_f32_e32 v109, 0x3f317218, v66
	v_fma_f32 v209, v67, s4, -v109
	v_add_f32_e32 v67, 1.0, v115
	v_log_f32_e32 v116, v67
	v_mul_f32_e32 v67, 0x3e000000, v69
	v_max_f32_e32 v66, 0, v111
	v_mul_f32_e64 v111, |v67|, s41
	v_mul_f32_e32 v115, 0x3e000000, v82
	v_exp_f32_e32 v111, v111
	v_mul_f32_e64 v117, |v115|, s41
	v_exp_f32_e32 v119, v117
	v_max_f32_e32 v149, 0, v115
	v_add_f32_e32 v111, 1.0, v111
	v_log_f32_e32 v117, v111
	v_add_f32_e32 v111, 1.0, v119
	v_mul_f32_e32 v119, 0x3e000000, v83
	v_mul_f32_e64 v121, |v119|, s41
	v_log_f32_e32 v111, v111
	v_exp_f32_e32 v121, v121
	v_mul_f32_e32 v115, 0x3e000000, v84
	v_max_f32_e32 v213, 0, v119
	v_fmac_f32_e32 v149, 0x3f317218, v111
	v_add_f32_e32 v111, 1.0, v121
	v_mul_f32_e64 v121, |v115|, s41
	v_log_f32_e32 v111, v111
	v_exp_f32_e32 v121, v121
	v_max_f32_e32 v151, 0, v115
	v_fma_f32 v82, v82, s4, -v149
	v_mul_f32_e32 v119, 0x3f317218, v111
	v_add_f32_e32 v111, 1.0, v121
	v_log_f32_e32 v197, v111
	v_mul_f32_e32 v111, 0x3e000000, v85
	v_mul_f32_e64 v115, |v111|, s41
	v_mul_f32_e32 v121, 0x3e000000, v78
	v_exp_f32_e32 v115, v115
	v_mul_f32_e64 v123, |v121|, s41
	v_exp_f32_e32 v123, v123
	v_max_f32_e32 v199, 0, v111
	v_add_f32_e32 v111, 1.0, v115
	v_mul_f32_e32 v115, 0x3e000000, v79
	v_log_f32_e32 v211, v111
	v_add_f32_e32 v111, 1.0, v123
	v_mul_f32_e64 v123, |v115|, s41
	v_log_f32_e32 v111, v111
	v_exp_f32_e32 v123, v123
	v_max_f32_e32 v147, 0, v121
	v_mul_f32_e32 v121, 0x3e000000, v80
	v_fmac_f32_e32 v147, 0x3f317218, v111
	v_add_f32_e32 v111, 1.0, v123
	v_mul_f32_e64 v123, |v121|, s41
	v_log_f32_e32 v111, v111
	v_exp_f32_e32 v123, v123
	v_max_f32_e32 v215, 0, v115
	v_max_f32_e32 v139, 0, v121
	v_mul_f32_e32 v135, 0x3f317218, v111
	v_add_f32_e32 v111, 1.0, v123
	v_log_f32_e32 v143, v111
	v_mul_f32_e32 v111, 0x3e000000, v81
	v_mul_f32_e64 v115, |v111|, s41
	v_mul_f32_e32 v121, 0x3e000000, v74
	v_exp_f32_e32 v115, v115
	v_mul_f32_e64 v123, |v121|, s41
	v_exp_f32_e32 v123, v123
	v_max_f32_e32 v137, 0, v111
	v_add_f32_e32 v111, 1.0, v115
	v_mul_f32_e32 v115, 0x3e000000, v75
	v_log_f32_e32 v141, v111
	v_add_f32_e32 v111, 1.0, v123
	v_mul_f32_e64 v123, |v115|, s41
	v_log_f32_e32 v111, v111
	v_exp_f32_e32 v123, v123
	v_max_f32_e32 v127, 0, v121
	v_max_f32_e32 v217, 0, v115
	v_fmac_f32_e32 v127, 0x3f317218, v111
	v_add_f32_e32 v111, 1.0, v123
	v_log_f32_e32 v111, v111
	v_pk_add_f32 v[218:219], v[0:1], v[148:149]
	v_pk_fma_f32 v[148:149], v[196:197], s[30:31], v[150:151] op_sel_hi:[1,0,1]
	v_pk_fma_f32 v[150:151], v[210:211], s[30:31], v[198:199] op_sel_hi:[1,0,1]
	v_mul_f32_e32 v115, 0x3f317218, v111
	v_mul_f32_e32 v111, 0x3e000000, v76
	v_mul_f32_e64 v121, |v111|, s41
	v_exp_f32_e32 v123, v121
	v_max_f32_e32 v121, 0, v111
	v_mul_f32_e32 v111, 0x3e000000, v77
	v_mul_f32_e64 v129, |v111|, s41
	v_exp_f32_e32 v131, v129
	v_max_f32_e32 v129, 0, v111
	v_pk_add_f32 v[198:199], v[212:213], v[118:119]
	v_fma_f32 v0, v91, s4, -v218
	v_add_f32_e32 v111, 1.0, v131
	v_log_f32_e32 v131, v111
	v_cndmask_b32_e64 v111, v193, v90, s[10:11]
	v_fma_f32 v90, v92, s4, -v148
	v_cndmask_b32_e64 v227, v193, v90, s[16:17]
	v_fma_f32 v90, v93, s4, -v150
	v_cndmask_b32_e64 v228, v193, v90, s[18:19]
	v_cndmask_b32_e64 v197, 0, v219, s[94:95]
	v_cndmask_b32_e64 v196, 0, v218, s[14:15]
	v_cndmask_b32_e64 v91, 0, v199, s[96:97]
	v_cndmask_b32_e64 v90, 0, v198, s[10:11]
	v_pk_add_f32 v[118:119], v[196:197], v[90:91]
	v_cndmask_b32_e64 v93, 0, v149, s[98:99]
	v_cndmask_b32_e64 v92, 0, v148, s[16:17]
	v_pk_add_f32 v[144:145], v[144:145], v[146:147]
	v_pk_add_f32 v[210:211], v[92:93], v[118:119]
	v_cndmask_b32_e64 v118, 0, v150, s[18:19]
	s_or_b64 s[18:19], s[76:77], vcc
	v_fma_f32 v87, v87, s4, -v144
	s_or_b64 s[16:17], s[72:73], vcc
	v_fma_f32 v78, v78, s4, -v147
	v_cndmask_b32_e64 v0, v193, v0, s[14:15]
	v_cndmask_b32_e64 v90, v193, v113, s[18:19]
	v_cndmask_b32_e64 v113, v193, v87, s[16:17]
	v_pk_fma_f32 v[142:143], v[142:143], s[30:31], v[138:139] op_sel_hi:[1,0,1]
	s_or_b64 s[14:15], s[70:71], vcc
	v_cndmask_b32_e64 v144, 0, v144, s[16:17]
	v_pk_add_f32 v[146:147], v[214:215], v[134:135]
	s_or_b64 s[16:17], s[74:75], vcc
	s_or_b64 s[10:11], s[66:67], vcc
	v_fma_f32 v87, v88, s4, -v142
	v_pk_fma_f32 v[140:141], v[140:141], s[30:31], v[136:137] op_sel_hi:[1,0,1]
	v_cndmask_b32_e64 v145, 0, v145, s[14:15]
	v_cndmask_b32_e64 v135, 0, v147, s[16:17]
	v_cndmask_b32_e64 v134, 0, v146, s[18:19]
	s_or_b64 s[18:19], s[78:79], vcc
	v_cndmask_b32_e64 v119, 0, v151, s[10:11]
	v_cndmask_b32_e64 v148, v193, v87, s[20:21]
	v_fma_f32 v87, v89, s4, -v140
	v_pk_add_f32 v[88:89], v[144:145], v[134:135]
	v_cndmask_b32_e64 v137, 0, v143, s[18:19]
	v_cndmask_b32_e64 v136, 0, v142, s[20:21]
	s_or_b64 s[20:21], s[82:83], vcc
	v_pk_add_f32 v[210:211], v[118:119], v[210:211]
	v_pk_add_f32 v[88:89], v[136:137], v[88:89]
	v_cndmask_b32_e64 v139, 0, v141, s[20:21]
	v_cndmask_b32_e64 v138, 0, v140, s[22:23]
	ds_bpermute_b32 v212, v204, v210
	ds_bpermute_b32 v213, v204, v211
	v_pk_add_f32 v[88:89], v[138:139], v[88:89]
	ds_bpermute_b32 v214, v204, v88
	ds_bpermute_b32 v215, v204, v89
	v_add_f32_e32 v123, 1.0, v123
	s_waitcnt lgkmcnt(2)
	v_pk_add_f32 v[210:211], v[210:211], v[212:213]
	ds_bpermute_b32 v218, v203, v210
	v_log_f32_e32 v123, v123
	s_waitcnt lgkmcnt(1)
	v_pk_add_f32 v[220:221], v[88:89], v[214:215]
	ds_bpermute_b32 v222, v203, v220
	v_cndmask_b32_e64 v150, v193, v87, s[22:23]
	v_cndmask_b32_e64 v87, 0, v212, s[44:45]
	s_waitcnt lgkmcnt(1)
	v_cndmask_b32_e64 v88, 0, v218, s[46:47]
	v_add_f32_e32 v134, v87, v88
	v_cndmask_b32_e64 v87, 0, v214, s[44:45]
	s_waitcnt lgkmcnt(0)
	v_cndmask_b32_e64 v88, 0, v222, s[46:47]
	v_add_f32_e32 v140, v87, v88
	v_mov_b32_e32 v87, v1
	v_fma_f32 v74, v74, s4, -v127
	v_pk_add_f32 v[86:87], v[86:87], v[126:127]
	v_pk_fma_f32 v[126:127], v[130:131], s[30:31], v[128:129] op_sel_hi:[1,0,1]
	v_pk_add_f32 v[130:131], v[216:217], v[114:115]
	v_cndmask_b32_e64 v74, v193, v74, s[12:13]
	v_pk_fma_f32 v[122:123], v[122:123], s[30:31], v[120:121] op_sel_hi:[1,0,1]
	v_cndmask_b32_e64 v129, 0, v87, s[12:13]
	v_cndmask_b32_e32 v128, 0, v86, vcc
	v_cndmask_b32_e64 v89, 0, v131, s[24:25]
	v_cndmask_b32_e32 v88, 0, v130, vcc
	s_or_b64 s[12:13], s[90:91], vcc
	v_pk_add_f32 v[120:121], v[128:129], v[88:89]
	v_cndmask_b32_e64 v115, 0, v123, s[12:13]
	v_cndmask_b32_e32 v114, 0, v122, vcc
	s_or_b64 s[22:23], s[92:93], vcc
	v_pk_add_f32 v[216:217], v[114:115], v[120:121]
	v_cndmask_b32_e64 v121, 0, v127, s[22:23]
	v_cndmask_b32_e32 v120, 0, v126, vcc
	v_pk_add_f32 v[216:217], v[120:121], v[216:217]
	ds_bpermute_b32 v224, v204, v216
	ds_bpermute_b32 v225, v204, v217
	v_fma_f32 v71, v71, s4, -v86
	ds_bpermute_b32 v219, v203, v211
	ds_bpermute_b32 v223, v203, v221
	v_fma_f32 v72, v72, s4, -v122
	s_waitcnt lgkmcnt(2)
	v_pk_add_f32 v[86:87], v[216:217], v[224:225]
	ds_bpermute_b32 v216, v203, v86
	ds_bpermute_b32 v217, v203, v87
	v_cndmask_b32_e32 v88, v193, v72, vcc
	v_fma_f32 v72, v73, s4, -v126
	v_cndmask_b32_e32 v122, v193, v72, vcc
	v_cndmask_b32_e64 v72, 0, v224, s[44:45]
	s_waitcnt lgkmcnt(1)
	v_cndmask_b32_e64 v73, 0, v216, s[46:47]
	s_waitcnt lgkmcnt(0)
	v_pk_add_f32 v[86:87], v[86:87], v[216:217]
	v_add_f32_e32 v126, v72, v73
	v_pk_add_f32 v[72:73], v[210:211], v[218:219]
	v_pk_add_f32 v[210:211], v[220:221], v[222:223]
	v_pk_add_f32 v[220:221], v[106:107], v[86:87]
	v_add_f32_e32 v106, v106, v126
	v_pk_add_f32 v[210:211], v[210:211], v[220:221]
	v_add_f32_e32 v120, v120, v106
	v_pk_add_f32 v[86:87], v[72:73], v[210:211]
	v_add_f32_e32 v72, v134, v210
	v_add_f32_e32 v73, v118, v72
	v_add_f32_e32 v92, v92, v73
	v_add_f32_e32 v118, v196, v92
	v_sub_f32_e32 v0, v0, v92
	v_sub_f32_e32 v92, v111, v118
	v_add_f32_e32 v111, v140, v220
	v_add_f32_e32 v118, v138, v111
	v_sub_f32_e32 v72, v228, v72
	v_sub_f32_e32 v73, v227, v73
	v_add_f32_e32 v129, v136, v118
	v_sub_f32_e32 v106, v122, v106
	v_sub_f32_e32 v88, v88, v120
	v_mul_f32_e32 v72, 0x3fb8aa3b, v72
	v_mul_f32_e32 v73, 0x3fb8aa3b, v73
	v_mul_f32_e32 v0, 0x3fb8aa3b, v0
	v_mul_f32_e32 v92, 0x3fb8aa3b, v92
	v_add_f32_e32 v130, v144, v129
	v_mul_f32_e32 v106, 0x3fb8aa3b, v106
	v_mul_f32_e32 v88, 0x3fb8aa3b, v88
	v_exp_f32_e32 v72, v72
	v_exp_f32_e32 v73, v73
	v_exp_f32_e32 v0, v0
	v_exp_f32_e32 v92, v92
	v_sub_f32_e32 v113, v113, v129
	v_sub_f32_e32 v90, v90, v130
	v_exp_f32_e32 v106, v106
	v_exp_f32_e32 v88, v88
	v_mul_f32_e32 v113, 0x3fb8aa3b, v113
	v_mul_f32_e32 v90, 0x3fb8aa3b, v90
	v_add_f32_e32 v114, v114, v120
	v_cndmask_b32_e32 v71, v193, v71, vcc
	v_sub_f32_e32 v111, v150, v111
	v_sub_f32_e32 v118, v148, v118
	v_exp_f32_e32 v113, v113
	v_exp_f32_e32 v90, v90
	v_add_f32_e32 v126, v128, v114
	v_mul_f32_e32 v111, 0x3fb8aa3b, v111
	v_mul_f32_e32 v118, 0x3fb8aa3b, v118
	v_sub_f32_e32 v71, v71, v114
	v_sub_f32_e32 v70, v70, v126
	v_exp_f32_e32 v111, v111
	v_exp_f32_e32 v118, v118
	v_mul_f32_e32 v71, 0x3fb8aa3b, v71
	v_mul_f32_e32 v70, 0x3fb8aa3b, v70
	v_cvt_pk_bf16_f32 v128, v92, v0
	v_cvt_pk_bf16_f32 v129, v73, v72
	v_cvt_pk_bf16_f32 v73, v88, v106
	v_cndmask_b32_e64 v0, v193, v82, s[94:95]
	v_fma_f32 v82, v83, s4, -v199
	v_fma_f32 v83, v84, s4, -v149
	v_fma_f32 v84, v85, s4, -v151
	v_cndmask_b32_e64 v85, 0, v213, s[44:45]
	v_cndmask_b32_e64 v88, 0, v219, s[46:47]
	v_exp_f32_e32 v114, v71
	v_exp_f32_e32 v120, v70
	v_add_f32_e32 v85, v85, v88
	v_cndmask_b32_e64 v88, v193, v78, s[14:15]
	v_fma_f32 v78, v79, s4, -v147
	v_max_f32_e32 v67, 0, v67
	v_cvt_pk_bf16_f32 v70, v90, v113
	v_cndmask_b32_e64 v90, v193, v78, s[16:17]
	v_fma_f32 v78, v80, s4, -v143
	v_cndmask_b32_e64 v92, v193, v78, s[18:19]
	v_fma_f32 v78, v81, s4, -v141
	v_pk_fma_f32 v[66:67], v[116:117], s[30:31], v[66:67] op_sel_hi:[1,0,1]
	v_pk_add_f32 v[132:133], v[108:109], v[132:133]
	v_cvt_pk_bf16_f32 v71, v118, v111
	v_cndmask_b32_e64 v106, v193, v78, s[20:21]
	v_cndmask_b32_e64 v78, 0, v215, s[44:45]
	v_cndmask_b32_e64 v79, 0, v223, s[46:47]
	v_mov_b32_e32 v111, v66
	v_cvt_pk_bf16_f32 v72, v120, v114
	v_add_f32_e32 v114, v78, v79
	v_pk_add_f32 v[78:79], v[110:111], v[132:133]
	v_mov_b32_e32 v113, v67
	v_pk_add_f32 v[78:79], v[112:113], v[78:79]
	ds_bpermute_b32 v80, v204, v78
	ds_bpermute_b32 v81, v204, v79
	v_fma_f32 v76, v76, s4, -v123
	v_cndmask_b32_e64 v111, v193, v76, s[12:13]
	v_fma_f32 v76, v77, s4, -v127
	v_cndmask_b32_e64 v113, v193, v76, s[22:23]
	s_waitcnt lgkmcnt(0)
	v_pk_add_f32 v[116:117], v[78:79], v[80:81]
	ds_bpermute_b32 v122, v203, v116
	v_cndmask_b32_e64 v76, 0, v225, s[44:45]
	v_cndmask_b32_e64 v77, 0, v217, s[46:47]
	v_add_f32_e32 v76, v76, v77
	v_cndmask_b32_e64 v77, 0, v80, s[44:45]
	s_waitcnt lgkmcnt(0)
	v_cndmask_b32_e64 v78, 0, v122, s[46:47]
	v_add_f32_e32 v77, v77, v78
	v_add_f32_e32 v77, v77, v86
	v_add_f32_e32 v78, v112, v77
	v_add_f32_e32 v79, v110, v78
	v_sub_f32_e32 v77, v207, v77
	v_sub_f32_e32 v78, v206, v78
	v_mul_f32_e32 v77, 0x3fb8aa3b, v77
	v_mul_f32_e32 v78, 0x3fb8aa3b, v78
	ds_bpermute_b32 v123, v203, v117
	v_exp_f32_e32 v77, v77
	v_exp_f32_e32 v78, v78
	v_add_f32_e32 v80, v108, v79
	v_sub_f32_e32 v79, v205, v79
	v_sub_f32_e32 v80, v226, v80
	v_cvt_pk_bf16_f32 v127, v78, v77
	v_cndmask_b32_e64 v77, 0, v81, s[44:45]
	s_waitcnt lgkmcnt(0)
	v_cndmask_b32_e64 v78, 0, v123, s[46:47]
	v_add_f32_e32 v77, v77, v78
	v_add_f32_e32 v77, v77, v87
	v_mul_f32_e32 v79, 0x3fb8aa3b, v79
	v_mul_f32_e32 v80, 0x3fb8aa3b, v80
	v_fma_f32 v69, v69, s4, -v67
	v_add_f32_e32 v67, v77, v67
	v_exp_f32_e32 v79, v79
	v_exp_f32_e32 v80, v80
	v_add_f32_e32 v78, v66, v67
	v_fma_f32 v66, v68, s4, -v66
	v_sub_f32_e32 v66, v66, v67
	v_mul_f32_e32 v66, 0x3fb8aa3b, v66
	v_exp_f32_e32 v108, v66
	v_sub_f32_e32 v66, v209, v78
	v_cvt_pk_bf16_f32 v126, v80, v79
	v_add_f32_e32 v79, v109, v78
	v_mul_f32_e32 v66, 0x3fb8aa3b, v66
	v_exp_f32_e32 v78, v66
	v_sub_f32_e32 v66, v208, v79
	v_mul_f32_e32 v66, 0x3fb8aa3b, v66
	v_cndmask_b32_e64 v84, v193, v84, s[10:11]
	v_exp_f32_e32 v79, v66
	v_add_f32_e32 v66, v85, v211
	v_add_f32_e32 v67, v119, v66
	v_sub_f32_e32 v66, v84, v66
	v_cndmask_b32_e64 v83, v193, v83, s[98:99]
	v_mul_f32_e32 v66, 0x3fb8aa3b, v66
	v_exp_f32_e32 v84, v66
	v_sub_f32_e32 v66, v83, v67
	v_cndmask_b32_e64 v82, v193, v82, s[96:97]
	v_add_f32_e32 v68, v93, v67
	v_mul_f32_e32 v66, 0x3fb8aa3b, v66
	v_sub_f32_e32 v69, v69, v77
	v_exp_f32_e32 v85, v66
	v_sub_f32_e32 v66, v82, v68
	v_mul_f32_e32 v69, 0x3fb8aa3b, v69
	v_mul_f32_e32 v66, 0x3fb8aa3b, v66
	v_exp_f32_e32 v77, v69
	v_add_f32_e32 v69, v91, v68
	v_exp_f32_e32 v91, v66
	v_add_f32_e32 v66, v114, v221
	v_add_f32_e32 v67, v139, v66
	v_sub_f32_e32 v66, v106, v66
	v_mul_f32_e32 v66, 0x3fb8aa3b, v66
	v_exp_f32_e32 v93, v66
	v_sub_f32_e32 v66, v92, v67
	v_add_f32_e32 v68, v137, v67
	v_mul_f32_e32 v66, 0x3fb8aa3b, v66
	v_exp_f32_e32 v92, v66
	v_sub_f32_e32 v66, v90, v68
	v_sub_f32_e32 v0, v0, v69
	v_add_f32_e32 v69, v135, v68
	v_mul_f32_e32 v66, 0x3fb8aa3b, v66
	v_exp_f32_e32 v90, v66
	v_sub_f32_e32 v66, v88, v69
	v_lshl_add_u32 v88, v155, 1, v169
	v_add_u32_e32 v106, 0x2000, v88
	v_mul_f32_e32 v80, 0x3fb8aa3b, v66
	ds_read2_b64 v[66:69], v106 offset0:128 offset1:132
	v_add_u32_e32 v110, 0x2800, v88
	v_exp_f32_e32 v109, v80
	ds_read2_b64 v[80:83], v110 offset0:160 offset1:164
	v_mul_f32_e32 v0, 0x3fb8aa3b, v0
	v_exp_f32_e32 v0, v0
	v_add_f32_e32 v107, v107, v76
	v_cvt_pk_bf16_f32 v76, v79, v78
	v_cvt_pk_bf16_f32 v79, v85, v84
	s_waitcnt lgkmcnt(0)
	v_mov_b32_e32 v84, v80
	v_mov_b32_e32 v85, v81
	v_cvt_pk_bf16_f32 v77, v108, v77
	v_cvt_pk_bf16_f32 v78, v0, v91
	v_add_u32_e32 v108, 0x3000, v88
	s_setprio 3
	v_mfma_f32_16x16x32_bf16 v[62:65], v[66:69], v[126:129], v[62:65]
	v_sub_f32_e32 v80, v113, v107
	v_add_u32_e32 v88, 0x3800, v88
	v_add_f32_e32 v0, v121, v107
	v_mfma_f32_16x16x32_bf16 v[54:57], v[66:69], v[76:79], v[54:57]
	ds_read2_b64 v[66:69], v108 offset0:200 offset1:204
	v_mul_f32_e32 v107, 0x3fb8aa3b, v80
	v_fma_f32 v75, v75, s4, -v131
	v_mfma_f32_16x16x32_bf16 v[58:61], v[82:85], v[126:129], v[58:61]
	v_add_f32_e32 v91, v115, v0
	v_cndmask_b32_e64 v75, v193, v75, s[24:25]
	v_add_f32_e32 v89, v89, v91
	v_mfma_f32_16x16x32_bf16 v[46:49], v[82:85], v[76:79], v[46:49]
	ds_read2_b64 v[80:83], v88 offset0:232 offset1:236
	v_sub_f32_e32 v0, v111, v0
	v_sub_f32_e32 v75, v75, v91
	s_waitcnt lgkmcnt(1)
	v_mfma_f32_16x16x32_bf16 v[50:53], v[66:69], v[126:129], v[50:53]
	v_sub_f32_e32 v74, v74, v89
	s_waitcnt lgkmcnt(0)
	v_mov_b32_e32 v84, v80
	v_mov_b32_e32 v85, v81
	v_mfma_f32_16x16x32_bf16 v[42:45], v[66:69], v[76:79], v[42:45]
	ds_read2_b64 v[66:69], v106 offset0:136 offset1:140
	v_mul_f32_e32 v0, 0x3fb8aa3b, v0
	v_mul_f32_e32 v75, 0x3fb8aa3b, v75
	v_mul_f32_e32 v74, 0x3fb8aa3b, v74
	v_exp_f32_e32 v107, v107
	v_exp_f32_e32 v0, v0
	v_exp_f32_e32 v91, v75
	v_mfma_f32_16x16x32_bf16 v[34:37], v[82:85], v[76:79], v[34:37]
	v_exp_f32_e32 v76, v74
	ds_read2_b64 v[78:81], v110 offset0:168 offset1:172
	v_cvt_pk_bf16_f32 v74, v109, v90
	v_cvt_pk_bf16_f32 v75, v92, v93
	v_cvt_pk_bf16_f32 v76, v76, v91
	v_cvt_pk_bf16_f32 v77, v0, v107
	s_waitcnt lgkmcnt(1)
	v_mfma_f32_16x16x32_bf16 v[62:65], v[66:69], v[70:73], v[62:65]
	s_mov_b32 s10, 0x42b40000
	s_mov_b32 s97, 0x27c0000
	s_mov_b32 s96, 0x800000
	v_mfma_f32_16x16x32_bf16 v[54:57], v[66:69], v[74:77], v[54:57]
	s_waitcnt lgkmcnt(0)
	v_mov_b32_e32 v66, v80
	v_mov_b32_e32 v67, v81
	v_mov_b32_e32 v68, v78
	v_mov_b32_e32 v69, v79
	ds_read2_b64 v[78:81], v88 offset0:224 offset1:228
	v_mfma_f32_16x16x32_bf16 v[38:41], v[82:85], v[126:129], v[38:41]
	s_mov_b32 s30, 0x27e0000
	v_mfma_f32_16x16x32_bf16 v[58:61], v[66:69], v[70:73], v[58:61]
	v_mfma_f32_16x16x32_bf16 v[46:49], v[66:69], v[74:77], v[46:49]
	ds_read2_b64 v[66:69], v108 offset0:192 offset1:196
	s_waitcnt lgkmcnt(0)
	v_mfma_f32_16x16x32_bf16 v[50:53], v[66:69], v[70:73], v[50:53]
	v_mfma_f32_16x16x32_bf16 v[42:45], v[66:69], v[74:77], v[42:45]
	v_mov_b32_e32 v66, v80
	v_mov_b32_e32 v67, v81
	v_mov_b32_e32 v68, v78
	v_mov_b32_e32 v69, v79
	s_nop 1
	v_mfma_f32_16x16x32_bf16 v[38:41], v[66:69], v[70:73], v[38:41]
	v_add_f32_e64 v70, v116, v122
	v_add_f32_e64 v71, v117, v123
	v_pk_add_f32 v[106:107], v[70:71], v[86:87]
	v_mfma_f32_16x16x32_bf16 v[34:37], v[66:69], v[74:77], v[34:37]
	s_setprio 0
	v_cmp_lt_f32_e32 vcc, s10, v106
	v_cmp_lt_f32_e64 s[10:11], s10, v107
	s_and_b64 s[10:11], vcc, s[10:11]
	s_nop 0
	v_cndmask_b32_e64 v0, 0, 1, s[10:11]
	v_cmp_ne_u32_e32 vcc, 0, v0
	s_cmp_eq_u64 vcc, exec
	s_cselect_b64 s[10:11], -1, 0
	s_andn2_b64 s[12:13], s[38:39], exec
	s_and_b64 s[10:11], s[10:11], exec
	s_or_b64 s[38:39], s[12:13], s[10:11]
